# attention QK^T K-fragment ds_reads issued ahead of MFMAs, on top of bias interleave
# baseline (speedup 1.0000x reference)
; template <int D0> __device__ __forceinline__ void pv_one(f32x16& od, int vb, bf16x8 pa0, bf16x8 pa1, bf16x8 pa2, bf16x8 pa3) {
;   const s16x4 l0 = tr_read<v_rd_off(D0, 0, 0)>(vb), h0 = tr_read<v_rd_off(D0, 0, 1)>(vb), l1 = tr_read<v_rd_off(D0, 1, 0)>(vb), h1 = tr_read<v_rd_off(D0, 1, 1)>(vb);
;   const s16x4 l2 = tr_read<v_rd_off(D0, 2, 0)>(vb), h2 = tr_read<v_rd_off(D0, 2, 1)>(vb), l3 = tr_read<v_rd_off(D0, 3, 0)>(vb), h3 = tr_read<v_rd_off(D0, 3, 1)>(vb);
;   asm volatile("s_waitcnt lgkmcnt(0)" ::: "memory"); SBAR();
;     ...
;   od = __builtin_amdgcn_mfma_f32_32x32x16_bf16(pa0, PK(l0, h0), od, 0, 0, 0);
;   od = __builtin_amdgcn_mfma_f32_32x32x16_bf16(pa1, PK(l1, h1), od, 0, 0, 0);
;   od = __builtin_amdgcn_mfma_f32_32x32x16_bf16(pa2, PK(l2, h2), od, 0, 0, 0);
;   od = __builtin_amdgcn_mfma_f32_32x32x16_bf16(pa3, PK(l3, h3), od, 0, 0, 0);
;     ...
; }
; __device__ __forceinline__ void pv_d0(f32x16* o, int vb, bf16x8 pa0, bf16x8 pa1, bf16x8 pa2, bf16x8 pa3) {
;   pv_one<0>(o[0], vb, pa0, pa1, pa2, pa3); pv_one<1>(o[1], vb, pa0, pa1, pa2, pa3); pv_one<2>(o[2], vb, pa0, pa1, pa2, pa3); pv_one<3>(o[3], vb, pa0, pa1, pa2, pa3);
; }
; __device__ __forceinline__ void qkt_c(f32x16& p0, f32x16& p1, const char* Ks, const bf16x8* qr, const f32x16& negm, int r32, int hi) {
; #pragma unroll
;   for (int d0 = 0; d0 < 4; ++d0) { const int cb = (d0 * 16 + hi * 8) * 2;
;     bf16x8 b0 = *reinterpret_cast<const bf16x8*>(Ks + KSWZ(r32, cb));
;     bf16x8 b1 = *reinterpret_cast<const bf16x8*>(Ks + KSWZ(32 + r32, cb));
;     if (d0 == 0) { p0 = __builtin_amdgcn_mfma_f32_32x32x16_bf16(b0, qr[0], negm, 0, 0, 0); p1 = __builtin_amdgcn_mfma_f32_32x32x16_bf16(b1, qr[0], negm, 0, 0, 0); }
;     else { p0 = __builtin_amdgcn_mfma_f32_32x32x16_bf16(b0, qr[d0], p0, 0, 0, 0); p1 = __builtin_amdgcn_mfma_f32_32x32x16_bf16(b1, qr[d0], p1, 0, 0, 0); } }
; }
; template <int R> __device__ __forceinline__ void bias_r(f32x16& p0, f32x16& p1, float dq, float nslope) {
;   constexpr int C0 = (R & 3) + 8 * (R >> 2);
;   float x0, x1, a0 = p0[R], a1 = p1[R];
;   asm("v_sub_f32_e32 %0, %1, %2" : "=v"(x0) : "n"(__builtin_bit_cast(int, (float)C0)), "v"(dq));
;   asm("v_sub_f32_e32 %0, %1, %2" : "=v"(x1) : "n"(__builtin_bit_cast(int, (float)(C0 + 32))), "v"(dq));
;   asm("v_fma_f32 %0, %1, |%2|, %0" : "+v"(a0) : "v"(nslope), "v"(x0));
;   asm("v_fma_f32 %0, %1, |%2|, %0" : "+v"(a1) : "v"(nslope), "v"(x1));
.LBB0_364:
	ds_read_b128 v[114:117], v195 offset:32768
	ds_read_b128 v[204:207], v195 offset:40960
	ds_read_b128 v[208:211], v196 offset:32768
	ds_read_b128 v[212:215], v196 offset:40960
	ds_read_b128 v[216:219], v197 offset:32768
	ds_read_b128 v[220:223], v197 offset:40960
	s_and_b64 vcc, exec, s[14:15]
	s_waitcnt lgkmcnt(5)
	v_mfma_f32_32x32x16_bf16 v[98:113], v[114:117], v[130:133], v[82:97]
	s_waitcnt lgkmcnt(4)
	v_mfma_f32_32x32x16_bf16 v[114:129], v[204:207], v[130:133], v[82:97]
	ds_read_b128 v[204:207], v198 offset:32768
	s_waitcnt lgkmcnt(4)
	v_mfma_f32_32x32x16_bf16 v[98:113], v[208:211], v[134:137], v[98:113]
	ds_read_b128 v[208:211], v198 offset:40960
	s_waitcnt lgkmcnt(4)
	v_mfma_f32_32x32x16_bf16 v[114:129], v[212:215], v[134:137], v[114:129]
	s_waitcnt lgkmcnt(3)
	v_mfma_f32_32x32x16_bf16 v[98:113], v[216:219], v[138:141], v[98:113]
	s_waitcnt lgkmcnt(2)
	v_mfma_f32_32x32x16_bf16 v[114:129], v[220:223], v[138:141], v[114:129]
	s_waitcnt lgkmcnt(1)
	v_mfma_f32_32x32x16_bf16 v[98:113], v[204:207], v[142:145], v[98:113]
	s_waitcnt lgkmcnt(0)
	v_mfma_f32_32x32x16_bf16 v[114:129], v[208:211], v[142:145], v[114:129]
	s_cbranch_vccnz .LBB0_366
	s_add_i32 s72, s22, s46
	s_cmp_lt_i32 s46, s23
	s_cselect_b32 s14, s72, s39
	s_lshl_b32 s14, s14, 6
	v_cvt_f32_i32_e32 v0, s14
	v_sub_f32_e32 v0, v192, v0
	ds_read_b64_tr_b16 v[204:205], v194 offset:0
	ds_read_b64_tr_b16 v[206:207], v194 offset:0x800
	ds_read_b64_tr_b16 v[208:209], v194 offset:0x1000
	ds_read_b64_tr_b16 v[210:211], v194 offset:0x1800
	ds_read_b64_tr_b16 v[212:213], v194 offset:0x2000
	ds_read_b64_tr_b16 v[214:215], v194 offset:0x2800
	ds_read_b64_tr_b16 v[216:217], v194 offset:0x3000
	ds_read_b64_tr_b16 v[218:219], v194 offset:0x3800
	s_waitcnt lgkmcnt(0)
	s_nop 0
	v_mfma_f32_32x32x16_bf16 v[64:79], v[2:5], v[204:207], v[64:79]
	v_sub_f32_e32 v14, 0, v0
	v_sub_f32_e32 v15, 0x42000000, v0
	v_fma_f32 v98, v81, |v14|, v98
	v_sub_f32_e32 v14, 0x3f800000, v0
	ds_read_b64_tr_b16 v[204:205], v194 offset:0x200
	ds_read_b64_tr_b16 v[206:207], v194 offset:0xa00
	v_mfma_f32_32x32x16_bf16 v[64:79], v[6:9], v[208:211], v[64:79]
	v_fma_f32 v114, v81, |v15|, v114
	v_sub_f32_e32 v15, 0x42040000, v0
	v_fma_f32 v99, v81, |v14|, v99
	v_sub_f32_e32 v14, 0x40000000, v0
	ds_read_b64_tr_b16 v[208:209], v194 offset:0x1200
	ds_read_b64_tr_b16 v[210:211], v194 offset:0x1a00
	v_mfma_f32_32x32x16_bf16 v[64:79], v[10:13], v[212:215], v[64:79]
	v_fma_f32 v115, v81, |v15|, v115
	v_sub_f32_e32 v15, 0x42080000, v0
	v_fma_f32 v100, v81, |v14|, v100
	v_sub_f32_e32 v14, 0x40400000, v0
	ds_read_b64_tr_b16 v[212:213], v194 offset:0x2200
	ds_read_b64_tr_b16 v[214:215], v194 offset:0x2a00
	ds_read_b64_tr_b16 v[220:221], v194 offset:0x3200
	ds_read_b64_tr_b16 v[222:223], v194 offset:0x3a00
	s_waitcnt lgkmcnt(0)
	v_mfma_f32_32x32x16_bf16 v[64:79], v[162:165], v[216:219], v[64:79]
	v_fma_f32 v116, v81, |v15|, v116
	v_sub_f32_e32 v15, 0x420c0000, v0
	v_fma_f32 v101, v81, |v14|, v101
	v_sub_f32_e32 v14, 0x41000000, v0
	v_mfma_f32_32x32x16_bf16 v[48:63], v[2:5], v[204:207], v[48:63]
	v_fma_f32 v117, v81, |v15|, v117
	v_sub_f32_e32 v15, 0x42200000, v0
	v_fma_f32 v102, v81, |v14|, v102
	v_sub_f32_e32 v14, 0x41100000, v0
	ds_read_b64_tr_b16 v[204:205], v194 offset:0x400
	ds_read_b64_tr_b16 v[206:207], v194 offset:0xc00
	v_mfma_f32_32x32x16_bf16 v[48:63], v[6:9], v[208:211], v[48:63]
	v_fma_f32 v118, v81, |v15|, v118
	v_sub_f32_e32 v15, 0x42240000, v0
	v_fma_f32 v103, v81, |v14|, v103
	v_sub_f32_e32 v14, 0x41200000, v0
	ds_read_b64_tr_b16 v[208:209], v194 offset:0x1400
	ds_read_b64_tr_b16 v[210:211], v194 offset:0x1c00
	v_mfma_f32_32x32x16_bf16 v[48:63], v[10:13], v[212:215], v[48:63]
	v_fma_f32 v119, v81, |v15|, v119
	v_sub_f32_e32 v15, 0x42280000, v0
	v_fma_f32 v104, v81, |v14|, v104
	v_sub_f32_e32 v14, 0x41300000, v0
	ds_read_b64_tr_b16 v[212:213], v194 offset:0x2400
	ds_read_b64_tr_b16 v[214:215], v194 offset:0x2c00
	ds_read_b64_tr_b16 v[216:217], v194 offset:0x3400
	ds_read_b64_tr_b16 v[218:219], v194 offset:0x3c00
	s_waitcnt lgkmcnt(0)
	v_mfma_f32_32x32x16_bf16 v[48:63], v[162:165], v[220:223], v[48:63]
	v_fma_f32 v120, v81, |v15|, v120
	v_sub_f32_e32 v15, 0x422c0000, v0
	v_fma_f32 v105, v81, |v14|, v105
	v_sub_f32_e32 v14, 0x41800000, v0
	v_mfma_f32_32x32x16_bf16 v[32:47], v[2:5], v[204:207], v[32:47]
	v_fma_f32 v121, v81, |v15|, v121
	v_sub_f32_e32 v15, 0x42400000, v0
	v_fma_f32 v106, v81, |v14|, v106
	v_sub_f32_e32 v14, 0x41880000, v0
	ds_read_b64_tr_b16 v[204:205], v194 offset:0x600
	ds_read_b64_tr_b16 v[206:207], v194 offset:0xe00
	v_mfma_f32_32x32x16_bf16 v[32:47], v[6:9], v[208:211], v[32:47]
	v_fma_f32 v122, v81, |v15|, v122
	v_sub_f32_e32 v15, 0x42440000, v0
	v_fma_f32 v107, v81, |v14|, v107
	v_sub_f32_e32 v14, 0x41900000, v0
	ds_read_b64_tr_b16 v[208:209], v194 offset:0x1600
	ds_read_b64_tr_b16 v[210:211], v194 offset:0x1e00
	v_mfma_f32_32x32x16_bf16 v[32:47], v[10:13], v[212:215], v[32:47]
	v_fma_f32 v123, v81, |v15|, v123
	v_sub_f32_e32 v15, 0x42480000, v0
	v_fma_f32 v108, v81, |v14|, v108
	v_sub_f32_e32 v14, 0x41980000, v0
	ds_read_b64_tr_b16 v[212:213], v194 offset:0x2600
	ds_read_b64_tr_b16 v[214:215], v194 offset:0x2e00
	ds_read_b64_tr_b16 v[220:221], v194 offset:0x3600
	ds_read_b64_tr_b16 v[222:223], v194 offset:0x3e00
	s_waitcnt lgkmcnt(0)
	v_mfma_f32_32x32x16_bf16 v[32:47], v[162:165], v[216:219], v[32:47]
	v_fma_f32 v124, v81, |v15|, v124
	v_sub_f32_e32 v15, 0x424c0000, v0
	v_fma_f32 v109, v81, |v14|, v109
	v_sub_f32_e32 v14, 0x41c00000, v0
	v_mfma_f32_32x32x16_bf16 v[16:31], v[2:5], v[204:207], v[16:31]
	v_fma_f32 v125, v81, |v15|, v125
	v_sub_f32_e32 v15, 0x42600000, v0
	v_fma_f32 v110, v81, |v14|, v110
	v_sub_f32_e32 v14, 0x41c80000, v0
	v_mfma_f32_32x32x16_bf16 v[16:31], v[6:9], v[208:211], v[16:31]
	v_fma_f32 v126, v81, |v15|, v126
	v_sub_f32_e32 v15, 0x42640000, v0
	v_fma_f32 v111, v81, |v14|, v111
	v_sub_f32_e32 v14, 0x41d00000, v0
	v_mfma_f32_32x32x16_bf16 v[16:31], v[10:13], v[212:215], v[16:31]
	v_fma_f32 v127, v81, |v15|, v127
	v_sub_f32_e32 v15, 0x42680000, v0
	v_fma_f32 v112, v81, |v14|, v112
	v_sub_f32_e32 v14, 0x41d80000, v0
	v_mfma_f32_32x32x16_bf16 v[16:31], v[162:165], v[220:223], v[16:31]
	v_sub_f32_e32 v0, 0x426c0000, v0
	v_fma_f32 v128, v81, |v15|, v128
	v_fma_f32 v113, v81, |v14|, v113
	v_fma_f32 v129, v81, |v0|, v129
	s_barrier
	s_branch .Lafter_bias_0

; template <int D0> __device__ __forceinline__ void pv_one(f32x16& od, int vb, bf16x8 pa0, bf16x8 pa1, bf16x8 pa2, bf16x8 pa3) {
;   const s16x4 l0 = tr_read<v_rd_off(D0, 0, 0)>(vb), h0 = tr_read<v_rd_off(D0, 0, 1)>(vb), l1 = tr_read<v_rd_off(D0, 1, 0)>(vb), h1 = tr_read<v_rd_off(D0, 1, 1)>(vb);
;   const s16x4 l2 = tr_read<v_rd_off(D0, 2, 0)>(vb), h2 = tr_read<v_rd_off(D0, 2, 1)>(vb), l3 = tr_read<v_rd_off(D0, 3, 0)>(vb), h3 = tr_read<v_rd_off(D0, 3, 1)>(vb);
;   asm volatile("s_waitcnt lgkmcnt(0)" ::: "memory"); SBAR();
;     ...
;   od = __builtin_amdgcn_mfma_f32_32x32x16_bf16(pa0, PK(l0, h0), od, 0, 0, 0);
;   od = __builtin_amdgcn_mfma_f32_32x32x16_bf16(pa1, PK(l1, h1), od, 0, 0, 0);
;   od = __builtin_amdgcn_mfma_f32_32x32x16_bf16(pa2, PK(l2, h2), od, 0, 0, 0);
;   od = __builtin_amdgcn_mfma_f32_32x32x16_bf16(pa3, PK(l3, h3), od, 0, 0, 0);
;     ...
; }
; __device__ __forceinline__ void pv_d0(f32x16* o, int vb, bf16x8 pa0, bf16x8 pa1, bf16x8 pa2, bf16x8 pa3) {
;   pv_one<0>(o[0], vb, pa0, pa1, pa2, pa3); pv_one<1>(o[1], vb, pa0, pa1, pa2, pa3); pv_one<2>(o[2], vb, pa0, pa1, pa2, pa3); pv_one<3>(o[3], vb, pa0, pa1, pa2, pa3);
; }
; __device__ __forceinline__ void qkt_c(f32x16& p0, f32x16& p1, const char* Ks, const bf16x8* qr, const f32x16& negm, int r32, int hi) {
; #pragma unroll
;   for (int d0 = 0; d0 < 4; ++d0) { const int cb = (d0 * 16 + hi * 8) * 2;
;     bf16x8 b0 = *reinterpret_cast<const bf16x8*>(Ks + KSWZ(r32, cb));
;     bf16x8 b1 = *reinterpret_cast<const bf16x8*>(Ks + KSWZ(32 + r32, cb));
;     if (d0 == 0) { p0 = __builtin_amdgcn_mfma_f32_32x32x16_bf16(b0, qr[0], negm, 0, 0, 0); p1 = __builtin_amdgcn_mfma_f32_32x32x16_bf16(b1, qr[0], negm, 0, 0, 0); }
;     else { p0 = __builtin_amdgcn_mfma_f32_32x32x16_bf16(b0, qr[d0], p0, 0, 0, 0); p1 = __builtin_amdgcn_mfma_f32_32x32x16_bf16(b1, qr[d0], p1, 0, 0, 0); } }
; }
; template <int R> __device__ __forceinline__ void bias_r(f32x16& p0, f32x16& p1, float dq, float nslope) {
;   constexpr int C0 = (R & 3) + 8 * (R >> 2);
;   float x0, x1, a0 = p0[R], a1 = p1[R];
;   asm("v_sub_f32_e32 %0, %1, %2" : "=v"(x0) : "n"(__builtin_bit_cast(int, (float)C0)), "v"(dq));
;   asm("v_sub_f32_e32 %0, %1, %2" : "=v"(x1) : "n"(__builtin_bit_cast(int, (float)(C0 + 32))), "v"(dq));
;   asm("v_fma_f32 %0, %1, |%2|, %0" : "+v"(a0) : "v"(nslope), "v"(x0));
;   asm("v_fma_f32 %0, %1, |%2|, %0" : "+v"(a1) : "v"(nslope), "v"(x1));
.LBB0_379:
	s_waitcnt lgkmcnt(0)
	s_barrier
	ds_read_b128 v[114:117], v195 offset:49152
	ds_read_b128 v[204:207], v195 offset:57344
	ds_read_b128 v[208:211], v196 offset:49152
	ds_read_b128 v[212:215], v196 offset:57344
	ds_read_b128 v[216:219], v197 offset:49152
	ds_read_b128 v[220:223], v197 offset:57344
	s_andn2_b64 vcc, exec, s[14:15]
	s_waitcnt lgkmcnt(5)
	v_mfma_f32_32x32x16_bf16 v[98:113], v[114:117], v[130:133], v[82:97]
	s_waitcnt lgkmcnt(4)
	v_mfma_f32_32x32x16_bf16 v[114:129], v[204:207], v[130:133], v[82:97]
	ds_read_b128 v[204:207], v198 offset:49152
	s_waitcnt lgkmcnt(4)
	v_mfma_f32_32x32x16_bf16 v[98:113], v[208:211], v[134:137], v[98:113]
	ds_read_b128 v[208:211], v198 offset:57344
	s_waitcnt lgkmcnt(4)
	v_mfma_f32_32x32x16_bf16 v[114:129], v[212:215], v[134:137], v[114:129]
	s_waitcnt lgkmcnt(3)
	v_mfma_f32_32x32x16_bf16 v[98:113], v[216:219], v[138:141], v[98:113]
	s_waitcnt lgkmcnt(2)
	v_mfma_f32_32x32x16_bf16 v[114:129], v[220:223], v[138:141], v[114:129]
	s_waitcnt lgkmcnt(1)
	v_mfma_f32_32x32x16_bf16 v[98:113], v[204:207], v[142:145], v[98:113]
	s_waitcnt lgkmcnt(0)
	v_mfma_f32_32x32x16_bf16 v[114:129], v[208:211], v[142:145], v[114:129]
	s_cbranch_vccnz .LBB0_381
	s_add_i32 s46, s47, -1
	s_add_i32 s72, s72, 1
	s_add_i32 s14, s39, -1
	s_cmp_lt_i32 s46, s23
	s_cselect_b32 s14, s72, s14
	s_lshl_b32 s14, s14, 6
	v_cvt_f32_i32_e32 v0, s14
	v_sub_f32_e32 v0, v192, v0
	ds_read_b64_tr_b16 v[204:205], v193 offset:0
	ds_read_b64_tr_b16 v[206:207], v193 offset:0x800
	ds_read_b64_tr_b16 v[208:209], v193 offset:0x1000
	ds_read_b64_tr_b16 v[210:211], v193 offset:0x1800
	ds_read_b64_tr_b16 v[212:213], v193 offset:0x2000
	ds_read_b64_tr_b16 v[214:215], v193 offset:0x2800
	ds_read_b64_tr_b16 v[216:217], v193 offset:0x3000
	ds_read_b64_tr_b16 v[218:219], v193 offset:0x3800
	s_waitcnt lgkmcnt(0)
	s_nop 0
	v_mfma_f32_32x32x16_bf16 v[64:79], v[2:5], v[204:207], v[64:79]
	v_sub_f32_e32 v14, 0, v0
	v_sub_f32_e32 v15, 0x42000000, v0
	v_fma_f32 v98, v81, |v14|, v98
	v_sub_f32_e32 v14, 0x3f800000, v0
	ds_read_b64_tr_b16 v[204:205], v193 offset:0x200
	ds_read_b64_tr_b16 v[206:207], v193 offset:0xa00
	v_mfma_f32_32x32x16_bf16 v[64:79], v[6:9], v[208:211], v[64:79]
	v_fma_f32 v114, v81, |v15|, v114
	v_sub_f32_e32 v15, 0x42040000, v0
	v_fma_f32 v99, v81, |v14|, v99
	v_sub_f32_e32 v14, 0x40000000, v0
	ds_read_b64_tr_b16 v[208:209], v193 offset:0x1200
	ds_read_b64_tr_b16 v[210:211], v193 offset:0x1a00
	v_mfma_f32_32x32x16_bf16 v[64:79], v[10:13], v[212:215], v[64:79]
	v_fma_f32 v115, v81, |v15|, v115
	v_sub_f32_e32 v15, 0x42080000, v0
	v_fma_f32 v100, v81, |v14|, v100
	v_sub_f32_e32 v14, 0x40400000, v0
	ds_read_b64_tr_b16 v[212:213], v193 offset:0x2200
	ds_read_b64_tr_b16 v[214:215], v193 offset:0x2a00
	ds_read_b64_tr_b16 v[220:221], v193 offset:0x3200
	ds_read_b64_tr_b16 v[222:223], v193 offset:0x3a00
	s_waitcnt lgkmcnt(0)
	v_mfma_f32_32x32x16_bf16 v[64:79], v[162:165], v[216:219], v[64:79]
	v_fma_f32 v116, v81, |v15|, v116
	v_sub_f32_e32 v15, 0x420c0000, v0
	v_fma_f32 v101, v81, |v14|, v101
	v_sub_f32_e32 v14, 0x41000000, v0
	v_mfma_f32_32x32x16_bf16 v[48:63], v[2:5], v[204:207], v[48:63]
	v_fma_f32 v117, v81, |v15|, v117
	v_sub_f32_e32 v15, 0x42200000, v0
	v_fma_f32 v102, v81, |v14|, v102
	v_sub_f32_e32 v14, 0x41100000, v0
	ds_read_b64_tr_b16 v[204:205], v193 offset:0x400
	ds_read_b64_tr_b16 v[206:207], v193 offset:0xc00
	v_mfma_f32_32x32x16_bf16 v[48:63], v[6:9], v[208:211], v[48:63]
	v_fma_f32 v118, v81, |v15|, v118
	v_sub_f32_e32 v15, 0x42240000, v0
	v_fma_f32 v103, v81, |v14|, v103
	v_sub_f32_e32 v14, 0x41200000, v0
	ds_read_b64_tr_b16 v[208:209], v193 offset:0x1400
	ds_read_b64_tr_b16 v[210:211], v193 offset:0x1c00
	v_mfma_f32_32x32x16_bf16 v[48:63], v[10:13], v[212:215], v[48:63]
	v_fma_f32 v119, v81, |v15|, v119
	v_sub_f32_e32 v15, 0x42280000, v0
	v_fma_f32 v104, v81, |v14|, v104
	v_sub_f32_e32 v14, 0x41300000, v0
	ds_read_b64_tr_b16 v[212:213], v193 offset:0x2400
	ds_read_b64_tr_b16 v[214:215], v193 offset:0x2c00
	ds_read_b64_tr_b16 v[216:217], v193 offset:0x3400
	ds_read_b64_tr_b16 v[218:219], v193 offset:0x3c00
	s_waitcnt lgkmcnt(0)
	v_mfma_f32_32x32x16_bf16 v[48:63], v[162:165], v[220:223], v[48:63]
	v_fma_f32 v120, v81, |v15|, v120
	v_sub_f32_e32 v15, 0x422c0000, v0
	v_fma_f32 v105, v81, |v14|, v105
	v_sub_f32_e32 v14, 0x41800000, v0
	v_mfma_f32_32x32x16_bf16 v[32:47], v[2:5], v[204:207], v[32:47]
	v_fma_f32 v121, v81, |v15|, v121
	v_sub_f32_e32 v15, 0x42400000, v0
	v_fma_f32 v106, v81, |v14|, v106
	v_sub_f32_e32 v14, 0x41880000, v0
	ds_read_b64_tr_b16 v[204:205], v193 offset:0x600
	ds_read_b64_tr_b16 v[206:207], v193 offset:0xe00
	v_mfma_f32_32x32x16_bf16 v[32:47], v[6:9], v[208:211], v[32:47]
	v_fma_f32 v122, v81, |v15|, v122
	v_sub_f32_e32 v15, 0x42440000, v0
	v_fma_f32 v107, v81, |v14|, v107
	v_sub_f32_e32 v14, 0x41900000, v0
	ds_read_b64_tr_b16 v[208:209], v193 offset:0x1600
	ds_read_b64_tr_b16 v[210:211], v193 offset:0x1e00
	v_mfma_f32_32x32x16_bf16 v[32:47], v[10:13], v[212:215], v[32:47]
	v_fma_f32 v123, v81, |v15|, v123
	v_sub_f32_e32 v15, 0x42480000, v0
	v_fma_f32 v108, v81, |v14|, v108
	v_sub_f32_e32 v14, 0x41980000, v0
	ds_read_b64_tr_b16 v[212:213], v193 offset:0x2600
	ds_read_b64_tr_b16 v[214:215], v193 offset:0x2e00
	ds_read_b64_tr_b16 v[220:221], v193 offset:0x3600
	ds_read_b64_tr_b16 v[222:223], v193 offset:0x3e00
	s_waitcnt lgkmcnt(0)
	v_mfma_f32_32x32x16_bf16 v[32:47], v[162:165], v[216:219], v[32:47]
	v_fma_f32 v124, v81, |v15|, v124
	v_sub_f32_e32 v15, 0x424c0000, v0
	v_fma_f32 v109, v81, |v14|, v109
	v_sub_f32_e32 v14, 0x41c00000, v0
	v_mfma_f32_32x32x16_bf16 v[16:31], v[2:5], v[204:207], v[16:31]
	v_fma_f32 v125, v81, |v15|, v125
	v_sub_f32_e32 v15, 0x42600000, v0
	v_fma_f32 v110, v81, |v14|, v110
	v_sub_f32_e32 v14, 0x41c80000, v0
	v_mfma_f32_32x32x16_bf16 v[16:31], v[6:9], v[208:211], v[16:31]
	v_fma_f32 v126, v81, |v15|, v126
	v_sub_f32_e32 v15, 0x42640000, v0
	v_fma_f32 v111, v81, |v14|, v111
	v_sub_f32_e32 v14, 0x41d00000, v0
	v_mfma_f32_32x32x16_bf16 v[16:31], v[10:13], v[212:215], v[16:31]
	v_fma_f32 v127, v81, |v15|, v127
	v_sub_f32_e32 v15, 0x42680000, v0
	v_fma_f32 v112, v81, |v14|, v112
	v_sub_f32_e32 v14, 0x41d80000, v0
	v_mfma_f32_32x32x16_bf16 v[16:31], v[162:165], v[220:223], v[16:31]
	v_sub_f32_e32 v0, 0x426c0000, v0
	v_fma_f32 v128, v81, |v15|, v128
	v_fma_f32 v113, v81, |v14|, v113
	v_fma_f32 v129, v81, |v0|, v129
	s_barrier
	s_branch .Lafter_bias_1
